# hyena context direct-conv tap loops: overlap LDS reads with counted waits (same accumulation order)
# baseline (speedup 1.0000x reference)
; #define LAS __attribute__((address_space(3)))
; __global__ void __launch_bounds__(NTHR, 2) fwd_mega(Args a) {
;     ...
;                     for (int k = 0; k < 2; ++k) { const int i = tidc + 512 * k, b = i >> 8, t = i & 255; float acc = 0.f; const LAS float* kp = KC + 255 + t; const LAS float* up = U + b * 256;
; #pragma unroll 8
;                         for (int s = 0; s < 256; ++s) acc += kp[-s] * up[s];
;                         Z1[i] = XA[i] * (acc + bias1 * U[i]); }
.LBB0_624:
	v_add_u32_e32 v124, s10, v2
	ds_read2_b32 v[14:15], v124 offset0:6 offset1:7
	ds_read_b128 v[6:9], v5
	ds_read_b128 v[10:13], v5 offset:16
	s_sub_i32 s10, s10, 32
	v_add_u32_e32 v5, 32, v5
	s_cmpk_eq_i32 s10, 0xffe0
	s_waitcnt lgkmcnt(1)
	v_fmac_f32_e32 v3, v15, v6
	v_fmac_f32_e32 v3, v14, v7
	ds_read2_b32 v[14:15], v124 offset0:4 offset1:5
	ds_read2_b32 v[6:7], v124 offset0:2 offset1:3
	s_waitcnt lgkmcnt(1)
	v_fmac_f32_e32 v3, v15, v8
	v_fmac_f32_e32 v3, v14, v9
	ds_read2_b32 v[8:9], v124 offset1:1
	s_waitcnt lgkmcnt(1)
	v_fmac_f32_e32 v3, v7, v10
	v_fmac_f32_e32 v3, v6, v11
	s_waitcnt lgkmcnt(0)
	v_fmac_f32_e32 v3, v9, v12
	v_fmac_f32_e32 v3, v8, v13
	s_cbranch_scc0 .LBB0_624
	v_lshl_add_u32 v6, v4, 2, 0
	ds_read2st64_b32 v[4:5], v6 offset0:16 offset1:32
	s_movk_i32 s12, 0x200
	s_mov_b64 s[10:11], 0
	s_and_b64 vcc, exec, s[6:7]
	s_waitcnt lgkmcnt(0)
	v_fmac_f32_e32 v3, v165, v4
	v_mul_f32_e32 v3, v5, v3
	ds_write_b32 v6, v3 offset:16384
	s_cbranch_vccz .LBB0_623
	v_readlane_b32 s6, v254, 34
	s_mov_b32 s12, 0
	s_mov_b64 s[10:11], -1
	v_lshl_add_u32 v2, v0, 2, s6
	s_waitcnt lgkmcnt(0)
	s_barrier

; #define LAS __attribute__((address_space(3)))
; #define YHC ((float*)(wsb(a.ws) + WS_YHC))
; __global__ void __launch_bounds__(NTHR, 2) fwd_mega(Args a) {
;     ...
;                     for (int k = 0; k < 2; ++k) { const int i = tidc + 512 * k, b = i >> 8, t = i & 255; float acc = 0.f; const LAS float* kp = KC + 512 + 255 + t; const LAS float* up = Z1 + b * 256;
; #pragma unroll 8
;                         for (int s = 0; s < 256; ++s) acc += kp[-s] * up[s];
;                         YHC[((size_t)b * 256 + c) * 256 + t] = XB[i] * (acc + bias2 * Z1[i]); }
.LBB0_628:
	ds_read2_b32 v[124:125], v6 offset0:6 offset1:7
	v_add_u32_e32 v7, s10, v5
	ds_read_b128 v[8:11], v7
	ds_read_b128 v[12:15], v7 offset:16
	s_add_i32 s10, s10, 32
	s_cmpk_eq_i32 s10, 0x400
	s_waitcnt lgkmcnt(1)
	v_fmac_f32_e32 v3, v125, v8
	v_fmac_f32_e32 v3, v124, v9
	ds_read2_b32 v[124:125], v6 offset0:4 offset1:5
	ds_read2_b32 v[8:9], v6 offset0:2 offset1:3
	s_waitcnt lgkmcnt(1)
	v_fmac_f32_e32 v3, v125, v10
	v_fmac_f32_e32 v3, v124, v11
	ds_read2_b32 v[10:11], v6 offset1:1
	v_subrev_u32_e32 v6, 32, v6
	s_waitcnt lgkmcnt(1)
	v_fmac_f32_e32 v3, v9, v12
	v_fmac_f32_e32 v3, v8, v13
	s_waitcnt lgkmcnt(0)
	v_fmac_f32_e32 v3, v11, v14
	v_fmac_f32_e32 v3, v10, v15
	s_cbranch_scc0 .LBB0_628
	v_lshl_add_u32 v5, v4, 2, 0
	v_ashrrev_i32_e32 v4, 8, v4
	ds_read2st64_b32 v[6:7], v5 offset0:48 offset1:64
	v_ashrrev_i32_e32 v5, 31, v4
	s_mov_b64 s[10:11], s[58:59]
	v_lshlrev_b64 v[4:5], 18, v[4:5]
	v_lshlrev_b32_e32 v208, 2, v0
	v_lshl_add_u64 v[4:5], s[10:11], 0, v[4:5]
	v_lshl_add_u64 v[4:5], v[4:5], 0, s[4:5]
	v_lshl_add_u64 v[4:5], v[4:5], 0, v[208:209]
	v_add_co_u32_e32 v4, vcc, 0xf500000, v4
	s_waitcnt lgkmcnt(0)
	v_fmac_f32_e32 v3, v164, v7
	v_addc_co_u32_e32 v5, vcc, 0, v5, vcc
	v_mul_f32_e32 v3, v6, v3
	s_movk_i32 s12, 0x200
	s_mov_b64 s[10:11], 0
	s_and_b64 vcc, exec, s[6:7]
	global_store_dword v[4:5], v3, off
	s_cbranch_vccz .LBB0_627
	s_waitcnt lgkmcnt(0)
	s_barrier
	s_branch .LBB0_507
